# HGRN L2 prefetch distance 6 stages instead of 4
# baseline (speedup 1.0000x reference)
.LBB0_146:
	v_mov_b32_e32 v36, v188
	s_nop 0
	v_readfirstlane_b32 s0, v36
	s_ashr_i32 s12, s0, 6
	s_and_b32 s1, s3, 0x70
	s_and_b32 s14, s3, 7
	s_lshl_b32 s14, s14, 1
	s_or_b32 s1, s1, s14
	s_bfe_u32 s14, s3, 0x10003
	s_or_b32 s1, s1, s14
	s_lshl_b32 s0, s1, 6
	s_and_b32 s11, s0, 0x780
	s_and_b32 s10, s0, 64
	s_cmp_lt_u32 s1, 64
	s_cselect_b64 s[36:37], -1, 0
	s_lshl_b32 s0, s1, 8
	s_and_b32 s4, s0, 0x2000
	v_and_b32_e32 v110, 15, v36
	v_lshrrev_b32_e32 v104, 4, v36
	v_bfe_u32 v106, v36, 4, 2
	s_cmp_lt_i32 s12, 4
	s_mov_b64 s[0:1], -1
	s_cbranch_scc0 .LBB0_153
	s_and_b64 s[14:15], s[36:37], exec
	s_cselect_b32 s1, 0, 0x4000000
	s_add_u32 s1, s88, s1
	s_addc_u32 s13, s89, 0
	s_lshl_b32 s14, s11, 1
	s_add_u32 s1, s1, s14
	s_addc_u32 s13, s13, 0
	s_lshl_b32 s14, s10, 1
	s_add_u32 s1, s1, s14
	s_addc_u32 s13, s13, 0
	s_lshl_b32 s14, s12, 4
	s_ashr_i32 s15, s14, 31
	s_lshl_b64 s[14:15], s[14:15], 1
	s_waitcnt lgkmcnt(0)
	v_lshlrev_b32_e32 v2, 3, v106
	s_add_u32 s14, s1, s14
	s_movk_i32 s1, 0x90
	v_mad_u32_u24 v3, v110, s1, v2
	v_readlane_b32 s1, v247, 63
	s_mulk_i32 s12, 0x900
	s_addc_u32 s15, s13, s15
	v_add_u32_e32 v40, s1, v3
	s_add_i32 s1, s12, 0
	v_cmp_gt_u32_e32 vcc, 2, v106
	s_add_i32 s1, s1, 0xd000
	v_add_u32_e32 v41, s1, v3
	v_cndmask_b32_e64 v0, v195, 0, vcc
	s_movk_i32 s1, 0x110
	v_lshlrev_b32_e32 v1, 3, v104
	v_lshlrev_b32_e32 v96, 1, v110
	v_mad_u32_u24 v0, v110, s1, v0
	v_lshl_add_u64 v[32:33], s[14:15], 0, v[96:97]
	v_mul_u32_u24_e32 v3, 0x110, v110
	v_and_or_b32 v0, v1, 8, v0
	v_readlane_b32 s1, v248, 0
	v_mov_b32_e32 v96, v97
	v_lshlrev_b32_e32 v37, 2, v106
	v_add_u32_e32 v42, s1, v0
	v_add3_u32 v43, v3, v2, 0
	v_mov_b32_e32 v98, v97
	s_waitcnt vmcnt(0)
	v_mov_b32_e32 v99, v97
	v_mov_b64_e32 v[0:1], v[96:97]
	v_mov_b64_e32 v[4:5], v[96:97]
	v_mov_b64_e32 v[8:9], v[96:97]
	v_mov_b64_e32 v[12:13], v[96:97]
	v_mov_b64_e32 v[16:17], v[96:97]
	v_mov_b64_e32 v[20:21], v[96:97]
	v_mov_b64_e32 v[24:25], v[96:97]
	v_mov_b64_e32 v[28:29], v[96:97]
	v_mov_b64_e32 v[2:3], v[98:99]
	v_mov_b64_e32 v[6:7], v[98:99]
	v_mov_b64_e32 v[10:11], v[98:99]
	v_mov_b64_e32 v[14:15], v[98:99]
	v_mov_b64_e32 v[18:19], v[98:99]
	v_mov_b64_e32 v[22:23], v[98:99]
	v_mov_b64_e32 v[26:27], v[98:99]
	v_mov_b64_e32 v[30:31], v[98:99]
	v_lshl_add_u32 v38, v106, 4, s73
	v_xor_b32_e32 v39, 0x203c, v37
	s_lshl_b32 s1, s4, 12
	s_add_u32 s14, s14, s1
	s_addc_u32 s15, s15, 0
	s_mov_b32 s13, 0x10000
	s_cmp_lg_u64 s[36:37], 0
	s_cselect_b32 s13, s13, 0xffff0000
	s_ashr_i32 s1, s13, 4
	v_add_u32_e32 v58, 0xffffffc3, v39
	v_cndmask_b32_e64 v58, v58, v37, s[36:37]
	v_lshlrev_b32_e32 v58, 12, v58
	v_lshl_add_u32 v160, v110, 1, v58
	v_add_u32_e32 v161, s1, v160
	v_add_u32_e32 v162, s1, v161
	v_add_u32_e32 v163, s1, v162
	s_lshl_b32 s1, s11, 1
	s_add_u32 s16, s76, s1
	s_addc_u32 s17, s77, 0
	s_lshl_b32 s18, s13, 2
	v_and_b32_e32 v169, 63, v36
	v_lshrrev_b32_e32 v170, 6, v36
	v_lshlrev_b32_e32 v170, 4, v170
	v_bfe_u32 v171, v169, 1, 4
	v_add_u32_e32 v171, v170, v171
	v_and_b32_e32 v172, 15, v169
	v_add_u32_e32 v172, v170, v172
	v_sub_u32_e32 v170, 0x1fff, v171
	v_cndmask_b32_e64 v171, v170, v171, s[36:37]
	v_sub_u32_e32 v170, 0x1fff, v172
	v_cndmask_b32_e64 v172, v170, v172, s[36:37]
	v_add_u32_e32 v171, s4, v171
	v_add_u32_e32 v172, s4, v172
	v_lshlrev_b32_e32 v171, 12, v171
	v_lshlrev_b32_e32 v172, 12, v172
	v_and_b32_e32 v170, 1, v169
	v_lshl_or_b32 v171, v170, 7, v171
	s_mov_b32 s1, 0x8000000
	s_cmp_lg_u64 s[36:37], 0
	s_cselect_b32 s1, s1, 0xc000000
	v_mov_b32_e32 v170, s1
	v_cmp_gt_u32_e32 vcc, 32, v169
	s_nop 1
	v_cndmask_b32_e32 v170, 0, v170, vcc
	v_add_u32_e32 v171, v170, v171
	s_lshl_b32 s1, s10, 1
	s_add_u32 s1, s1, 0x4000000
	v_add_u32_e32 v172, s1, v172
	s_mul_i32 s1, s18, 7
	v_add_u32_e32 v171, s1, v171
	v_add_u32_e32 v172, s1, v172
	s_mov_b32 s0, 1
	s_barrier
.Lhc_stage:
	s_bitcmp1_b32 s0, 0
	s_cselect_b32 s12, 0, 0xfc00
	s_cmpk_gt_u32 s0, 0x79
	s_cbranch_scc1 .Lhc_nopf
	global_load_dword v167, v171, s[16:17]
	global_load_dword v168, v172, s[16:17]
	v_add_u32_e32 v171, s18, v171
	v_add_u32_e32 v172, s18, v172
